# grid.sync L1 invalidate hoisted before its spin; prefix-ready signal does a single-lane L2 write-back
# baseline (speedup 1.0000x reference)
.LBB0_150:
	s_or_b64 exec, exec, s[4:5]
	buffer_inv sc1
	s_nop 0
	s_nop 0
	s_nop 0
	s_nop 0
	s_nop 0
	s_nop 0
	s_nop 0
	s_nop 0
	s_nop 0
	s_nop 0
	s_nop 0
	s_nop 0
	s_nop 0
	s_nop 0
	v_mov_b32_e32 v0, 0
	global_load_dword v2, v0, s[2:3] offset:32 sc1
	v_and_b32_e32 v1, 0xffff0000, v1
	s_waitcnt vmcnt(0)
	v_and_b32_e32 v2, 0xffff0000, v2
	v_cmp_eq_u32_e32 vcc, v2, v1
	s_and_b64 exec, exec, vcc
	s_cbranch_execz .LBB0_153
	s_mov_b64 s[4:5], 0
.LBB0_152:
	s_sleep 1
	global_load_dword v2, v0, s[2:3] offset:32 sc1
	s_waitcnt vmcnt(0)
	v_and_b32_e32 v2, 0xffff0000, v2
	v_cmp_ne_u32_e32 vcc, v2, v1
	s_or_b64 s[4:5], vcc, s[4:5]
	s_andn2_b64 exec, exec, s[4:5]
	s_cbranch_execnz .LBB0_152
.LBB0_153:
	s_nop 0
	s_nop 0
.LBB0_154:
	s_or_b64 exec, exec, s[0:1]
	v_readlane_b32 s0, v253, 0
	v_readlane_b32 s2, v253, 2
	v_readlane_b32 s1, v253, 1
	v_readlane_b32 s3, v253, 3
	s_add_u32 s0, s2, 0xc0000
	s_addc_u32 s1, s3, 0
	v_writelane_b32 v254, s0, 3
	s_barrier
	s_nop 0
	v_writelane_b32 v254, s1, 4
	s_getreg_b32 s0, hwreg(HW_REG_XCC_ID, 0, 4)
	s_and_b32 s70, s0, 15
	s_mov_b64 s[0:1], exec
	v_readlane_b32 s2, v253, 6
	v_readlane_b32 s3, v253, 7
	s_and_b64 s[2:3], s[0:1], s[2:3]
	s_mov_b64 exec, s[2:3]
	s_cbranch_execz .LBB0_157
	s_mov_b64 s[2:3], exec
	v_mbcnt_lo_u32_b32 v0, s2, 0
	v_mbcnt_hi_u32_b32 v0, s3, v0
	v_cmp_eq_u32_e32 vcc, 0, v0
	s_and_b64 s[4:5], exec, vcc
	s_mov_b64 exec, s[4:5]
	s_cbranch_execz .LBB0_157
	s_bcnt1_i32_b64 s2, s[2:3]
	s_lshl_b32 s4, s70, 8
	v_mov_b32_e32 v1, s2
	v_readlane_b32 s2, v254, 3
	v_mov_b32_e32 v0, s4
	v_readlane_b32 s3, v254, 4
	s_nop 4
	global_atomic_add v0, v1, s[2:3] offset:1024

.Lpfx_loop:
	v_lshl_add_u64 v[2:3], v[8:9], 0, s[2:3]
	global_load_dword v16, v[2:3], off offset:-2816
	global_load_dword v17, v[2:3], off offset:-2560
	global_load_dword v18, v[2:3], off offset:-2304
	global_load_dword v19, v[2:3], off offset:-2048
	global_load_dword v20, v[2:3], off offset:-1792
	global_load_dword v21, v[2:3], off offset:-1536
	global_load_dword v22, v[2:3], off offset:-1280
	global_load_dword v23, v[2:3], off offset:-1024
	global_load_dword v24, v[2:3], off offset:-768
	global_load_dword v25, v[2:3], off offset:-512
	global_load_dword v26, v[2:3], off offset:-256
	global_load_dword v27, v[2:3], off offset:0
	global_load_dword v28, v[2:3], off offset:256
	global_load_dword v29, v[2:3], off offset:512
	global_load_dword v30, v[2:3], off offset:768
	global_load_dword v31, v[2:3], off offset:1024
	global_load_dword v32, v[2:3], off offset:1280
	global_load_dword v33, v[2:3], off offset:1536
	global_load_dword v34, v[2:3], off offset:1792
	global_load_dword v35, v[2:3], off offset:2048
	global_load_dword v36, v[2:3], off offset:2304
	global_load_dword v37, v[2:3], off offset:2560
	global_load_dword v38, v[2:3], off offset:2816
	global_load_dword v39, v[2:3], off offset:3072
	s_waitcnt vmcnt(48)
	global_store_dword v[8:9], v6, off offset:-2816
	global_store_dword v[8:9], v7, off offset:-2560
	v_mul_f32_e32 v10, v1, v7
	v_mul_f32_e32 v11, v1, v6
	v_fma_f32 v12, v0, v6, -v10
	v_fma_f32 v13, v0, v7, v11
	v_add_f32_e32 v14, v12, v40
	v_add_f32_e32 v15, v13, v41
	global_store_dword v[8:9], v14, off offset:-2304
	global_store_dword v[8:9], v15, off offset:-2048
	v_mul_f32_e32 v10, v1, v15
	v_mul_f32_e32 v11, v1, v14
	v_fma_f32 v12, v0, v14, -v10
	v_fma_f32 v13, v0, v15, v11
	v_add_f32_e32 v6, v12, v42
	v_add_f32_e32 v7, v13, v43
	global_store_dword v[8:9], v6, off offset:-1792
	global_store_dword v[8:9], v7, off offset:-1536
	v_mul_f32_e32 v10, v1, v7
	v_mul_f32_e32 v11, v1, v6
	v_fma_f32 v12, v0, v6, -v10
	v_fma_f32 v13, v0, v7, v11
	v_add_f32_e32 v14, v12, v44
	v_add_f32_e32 v15, v13, v45
	global_store_dword v[8:9], v14, off offset:-1280
	global_store_dword v[8:9], v15, off offset:-1024
	v_mul_f32_e32 v10, v1, v15
	v_mul_f32_e32 v11, v1, v14
	v_fma_f32 v12, v0, v14, -v10
	v_fma_f32 v13, v0, v15, v11
	v_add_f32_e32 v6, v12, v46
	v_add_f32_e32 v7, v13, v47
	global_store_dword v[8:9], v6, off offset:-768
	global_store_dword v[8:9], v7, off offset:-512
	v_mul_f32_e32 v10, v1, v7
	v_mul_f32_e32 v11, v1, v6
	v_fma_f32 v12, v0, v6, -v10
	v_fma_f32 v13, v0, v7, v11
	v_add_f32_e32 v14, v12, v48
	v_add_f32_e32 v15, v13, v49
	global_store_dword v[8:9], v14, off offset:-256
	global_store_dword v[8:9], v15, off offset:0
	v_mul_f32_e32 v10, v1, v15
	v_mul_f32_e32 v11, v1, v14
	v_fma_f32 v12, v0, v14, -v10
	v_fma_f32 v13, v0, v15, v11
	v_add_f32_e32 v6, v12, v50
	v_add_f32_e32 v7, v13, v51
	global_store_dword v[8:9], v6, off offset:256
	global_store_dword v[8:9], v7, off offset:512
	v_mul_f32_e32 v10, v1, v7
	v_mul_f32_e32 v11, v1, v6
	v_fma_f32 v12, v0, v6, -v10
	v_fma_f32 v13, v0, v7, v11
	v_add_f32_e32 v14, v12, v52
	v_add_f32_e32 v15, v13, v53
	global_store_dword v[8:9], v14, off offset:768
	global_store_dword v[8:9], v15, off offset:1024
	v_mul_f32_e32 v10, v1, v15
	v_mul_f32_e32 v11, v1, v14
	v_fma_f32 v12, v0, v14, -v10
	v_fma_f32 v13, v0, v15, v11
	v_add_f32_e32 v6, v12, v54
	v_add_f32_e32 v7, v13, v55
	global_store_dword v[8:9], v6, off offset:1280
	global_store_dword v[8:9], v7, off offset:1536
	v_mul_f32_e32 v10, v1, v7
	v_mul_f32_e32 v11, v1, v6
	v_fma_f32 v12, v0, v6, -v10
	v_fma_f32 v13, v0, v7, v11
	v_add_f32_e32 v14, v12, v56
	v_add_f32_e32 v15, v13, v57
	global_store_dword v[8:9], v14, off offset:1792
	global_store_dword v[8:9], v15, off offset:2048
	v_mul_f32_e32 v10, v1, v15
	v_mul_f32_e32 v11, v1, v14
	v_fma_f32 v12, v0, v14, -v10
	v_fma_f32 v13, v0, v15, v11
	v_add_f32_e32 v6, v12, v58
	v_add_f32_e32 v7, v13, v59
	global_store_dword v[8:9], v6, off offset:2304
	global_store_dword v[8:9], v7, off offset:2560
	v_mul_f32_e32 v10, v1, v7
	v_mul_f32_e32 v11, v1, v6
	v_fma_f32 v12, v0, v6, -v10
	v_fma_f32 v13, v0, v7, v11
	v_add_f32_e32 v14, v12, v60
	v_add_f32_e32 v15, v13, v61
	global_store_dword v[8:9], v14, off offset:2816
	global_store_dword v[8:9], v15, off offset:3072
	v_mul_f32_e32 v10, v1, v15
	v_mul_f32_e32 v11, v1, v14
	v_fma_f32 v12, v0, v14, -v10
	v_fma_f32 v13, v0, v15, v11
	v_add_f32_e32 v6, v12, v62
	v_add_f32_e32 v7, v13, v63
	v_lshl_add_u64 v[8:9], v[2:3], 0, s[2:3]
	global_load_dword v40, v[8:9], off offset:-2816
	global_load_dword v41, v[8:9], off offset:-2560
	global_load_dword v42, v[8:9], off offset:-2304
	global_load_dword v43, v[8:9], off offset:-2048
	global_load_dword v44, v[8:9], off offset:-1792
	global_load_dword v45, v[8:9], off offset:-1536
	global_load_dword v46, v[8:9], off offset:-1280
	global_load_dword v47, v[8:9], off offset:-1024
	global_load_dword v48, v[8:9], off offset:-768
	global_load_dword v49, v[8:9], off offset:-512
	global_load_dword v50, v[8:9], off offset:-256
	global_load_dword v51, v[8:9], off offset:0
	global_load_dword v52, v[8:9], off offset:256
	global_load_dword v53, v[8:9], off offset:512
	global_load_dword v54, v[8:9], off offset:768
	global_load_dword v55, v[8:9], off offset:1024
	global_load_dword v56, v[8:9], off offset:1280
	global_load_dword v57, v[8:9], off offset:1536
	global_load_dword v58, v[8:9], off offset:1792
	global_load_dword v59, v[8:9], off offset:2048
	global_load_dword v60, v[8:9], off offset:2304
	global_load_dword v61, v[8:9], off offset:2560
	global_load_dword v62, v[8:9], off offset:2816
	global_load_dword v63, v[8:9], off offset:3072
	s_waitcnt vmcnt(48)
	global_store_dword v[2:3], v6, off offset:-2816
	global_store_dword v[2:3], v7, off offset:-2560
	v_mul_f32_e32 v10, v1, v7
	v_mul_f32_e32 v11, v1, v6
	v_fma_f32 v12, v0, v6, -v10
	v_fma_f32 v13, v0, v7, v11
	v_add_f32_e32 v14, v12, v16
	v_add_f32_e32 v15, v13, v17
	global_store_dword v[2:3], v14, off offset:-2304
	global_store_dword v[2:3], v15, off offset:-2048
	v_mul_f32_e32 v10, v1, v15
	v_mul_f32_e32 v11, v1, v14
	v_fma_f32 v12, v0, v14, -v10
	v_fma_f32 v13, v0, v15, v11
	v_add_f32_e32 v6, v12, v18
	v_add_f32_e32 v7, v13, v19
	global_store_dword v[2:3], v6, off offset:-1792
	global_store_dword v[2:3], v7, off offset:-1536
	v_mul_f32_e32 v10, v1, v7
	v_mul_f32_e32 v11, v1, v6
	v_fma_f32 v12, v0, v6, -v10
	v_fma_f32 v13, v0, v7, v11
	v_add_f32_e32 v14, v12, v20
	v_add_f32_e32 v15, v13, v21
	global_store_dword v[2:3], v14, off offset:-1280
	global_store_dword v[2:3], v15, off offset:-1024
	v_mul_f32_e32 v10, v1, v15
	v_mul_f32_e32 v11, v1, v14
	v_fma_f32 v12, v0, v14, -v10
	v_fma_f32 v13, v0, v15, v11
	v_add_f32_e32 v6, v12, v22
	v_add_f32_e32 v7, v13, v23
	global_store_dword v[2:3], v6, off offset:-768
	global_store_dword v[2:3], v7, off offset:-512
	v_mul_f32_e32 v10, v1, v7
	v_mul_f32_e32 v11, v1, v6
	v_fma_f32 v12, v0, v6, -v10
	v_fma_f32 v13, v0, v7, v11
	v_add_f32_e32 v14, v12, v24
	v_add_f32_e32 v15, v13, v25
	global_store_dword v[2:3], v14, off offset:-256
	global_store_dword v[2:3], v15, off offset:0
	v_mul_f32_e32 v10, v1, v15
	v_mul_f32_e32 v11, v1, v14
	v_fma_f32 v12, v0, v14, -v10
	v_fma_f32 v13, v0, v15, v11
	v_add_f32_e32 v6, v12, v26
	v_add_f32_e32 v7, v13, v27
	global_store_dword v[2:3], v6, off offset:256
	global_store_dword v[2:3], v7, off offset:512
	v_mul_f32_e32 v10, v1, v7
	v_mul_f32_e32 v11, v1, v6
	v_fma_f32 v12, v0, v6, -v10
	v_fma_f32 v13, v0, v7, v11
	v_add_f32_e32 v14, v12, v28
	v_add_f32_e32 v15, v13, v29
	global_store_dword v[2:3], v14, off offset:768
	global_store_dword v[2:3], v15, off offset:1024
	v_mul_f32_e32 v10, v1, v15
	v_mul_f32_e32 v11, v1, v14
	v_fma_f32 v12, v0, v14, -v10
	v_fma_f32 v13, v0, v15, v11
	v_add_f32_e32 v6, v12, v30
	v_add_f32_e32 v7, v13, v31
	global_store_dword v[2:3], v6, off offset:1280
	global_store_dword v[2:3], v7, off offset:1536
	v_mul_f32_e32 v10, v1, v7
	v_mul_f32_e32 v11, v1, v6
	v_fma_f32 v12, v0, v6, -v10
	v_fma_f32 v13, v0, v7, v11
	v_add_f32_e32 v14, v12, v32
	v_add_f32_e32 v15, v13, v33
	global_store_dword v[2:3], v14, off offset:1792
	global_store_dword v[2:3], v15, off offset:2048
	v_mul_f32_e32 v10, v1, v15
	v_mul_f32_e32 v11, v1, v14
	v_fma_f32 v12, v0, v14, -v10
	v_fma_f32 v13, v0, v15, v11
	v_add_f32_e32 v6, v12, v34
	v_add_f32_e32 v7, v13, v35
	global_store_dword v[2:3], v6, off offset:2304
	global_store_dword v[2:3], v7, off offset:2560
	v_mul_f32_e32 v10, v1, v7
	v_mul_f32_e32 v11, v1, v6
	v_fma_f32 v12, v0, v6, -v10
	v_fma_f32 v13, v0, v7, v11
	v_add_f32_e32 v14, v12, v36
	v_add_f32_e32 v15, v13, v37
	global_store_dword v[2:3], v14, off offset:2816
	global_store_dword v[2:3], v15, off offset:3072
	v_mul_f32_e32 v10, v1, v15
	v_mul_f32_e32 v11, v1, v14
	v_fma_f32 v12, v0, v14, -v10
	v_fma_f32 v13, v0, v15, v11
	v_add_f32_e32 v6, v12, v38
	v_add_f32_e32 v7, v13, v39
	s_add_i32 s4, s4, -1
	s_cmp_lg_u32 s4, 0
	s_cbranch_scc1 .Lpfx_loop
	v_lshl_add_u64 v[2:3], v[8:9], 0, s[2:3]
	global_load_dword v16, v[2:3], off offset:-2816
	global_load_dword v17, v[2:3], off offset:-2560
	global_load_dword v18, v[2:3], off offset:-2304
	global_load_dword v19, v[2:3], off offset:-2048
	global_load_dword v20, v[2:3], off offset:-1792
	global_load_dword v21, v[2:3], off offset:-1536
	global_load_dword v22, v[2:3], off offset:-1280
	global_load_dword v23, v[2:3], off offset:-1024
	global_load_dword v24, v[2:3], off offset:-768
	global_load_dword v25, v[2:3], off offset:-512
	global_load_dword v26, v[2:3], off offset:-256
	global_load_dword v27, v[2:3], off offset:0
	global_load_dword v28, v[2:3], off offset:256
	global_load_dword v29, v[2:3], off offset:512
	global_load_dword v30, v[2:3], off offset:768
	global_load_dword v31, v[2:3], off offset:1024
	global_load_dword v32, v[2:3], off offset:1280
	global_load_dword v33, v[2:3], off offset:1536
	global_load_dword v34, v[2:3], off offset:1792
	global_load_dword v35, v[2:3], off offset:2048
	global_load_dword v36, v[2:3], off offset:2304
	global_load_dword v37, v[2:3], off offset:2560
	global_load_dword v38, v[2:3], off offset:2816
	global_load_dword v39, v[2:3], off offset:3072
	s_waitcnt vmcnt(48)
	global_store_dword v[8:9], v6, off offset:-2816
	global_store_dword v[8:9], v7, off offset:-2560
	v_mul_f32_e32 v10, v1, v7
	v_mul_f32_e32 v11, v1, v6
	v_fma_f32 v12, v0, v6, -v10
	v_fma_f32 v13, v0, v7, v11
	v_add_f32_e32 v14, v12, v40
	v_add_f32_e32 v15, v13, v41
	global_store_dword v[8:9], v14, off offset:-2304
	global_store_dword v[8:9], v15, off offset:-2048
	v_mul_f32_e32 v10, v1, v15
	v_mul_f32_e32 v11, v1, v14
	v_fma_f32 v12, v0, v14, -v10
	v_fma_f32 v13, v0, v15, v11
	v_add_f32_e32 v6, v12, v42
	v_add_f32_e32 v7, v13, v43
	global_store_dword v[8:9], v6, off offset:-1792
	global_store_dword v[8:9], v7, off offset:-1536
	v_mul_f32_e32 v10, v1, v7
	v_mul_f32_e32 v11, v1, v6
	v_fma_f32 v12, v0, v6, -v10
	v_fma_f32 v13, v0, v7, v11
	v_add_f32_e32 v14, v12, v44
	v_add_f32_e32 v15, v13, v45
	global_store_dword v[8:9], v14, off offset:-1280
	global_store_dword v[8:9], v15, off offset:-1024
	v_mul_f32_e32 v10, v1, v15
	v_mul_f32_e32 v11, v1, v14
	v_fma_f32 v12, v0, v14, -v10
	v_fma_f32 v13, v0, v15, v11
	v_add_f32_e32 v6, v12, v46
	v_add_f32_e32 v7, v13, v47
	global_store_dword v[8:9], v6, off offset:-768
	global_store_dword v[8:9], v7, off offset:-512
	v_mul_f32_e32 v10, v1, v7
	v_mul_f32_e32 v11, v1, v6
	v_fma_f32 v12, v0, v6, -v10
	v_fma_f32 v13, v0, v7, v11
	v_add_f32_e32 v14, v12, v48
	v_add_f32_e32 v15, v13, v49
	global_store_dword v[8:9], v14, off offset:-256
	global_store_dword v[8:9], v15, off offset:0
	v_mul_f32_e32 v10, v1, v15
	v_mul_f32_e32 v11, v1, v14
	v_fma_f32 v12, v0, v14, -v10
	v_fma_f32 v13, v0, v15, v11
	v_add_f32_e32 v6, v12, v50
	v_add_f32_e32 v7, v13, v51
	global_store_dword v[8:9], v6, off offset:256
	global_store_dword v[8:9], v7, off offset:512
	v_mul_f32_e32 v10, v1, v7
	v_mul_f32_e32 v11, v1, v6
	v_fma_f32 v12, v0, v6, -v10
	v_fma_f32 v13, v0, v7, v11
	v_add_f32_e32 v14, v12, v52
	v_add_f32_e32 v15, v13, v53
	global_store_dword v[8:9], v14, off offset:768
	global_store_dword v[8:9], v15, off offset:1024
	v_mul_f32_e32 v10, v1, v15
	v_mul_f32_e32 v11, v1, v14
	v_fma_f32 v12, v0, v14, -v10
	v_fma_f32 v13, v0, v15, v11
	v_add_f32_e32 v6, v12, v54
	v_add_f32_e32 v7, v13, v55
	global_store_dword v[8:9], v6, off offset:1280
	global_store_dword v[8:9], v7, off offset:1536
	v_mul_f32_e32 v10, v1, v7
	v_mul_f32_e32 v11, v1, v6
	v_fma_f32 v12, v0, v6, -v10
	v_fma_f32 v13, v0, v7, v11
	v_add_f32_e32 v14, v12, v56
	v_add_f32_e32 v15, v13, v57
	global_store_dword v[8:9], v14, off offset:1792
	global_store_dword v[8:9], v15, off offset:2048
	v_mul_f32_e32 v10, v1, v15
	v_mul_f32_e32 v11, v1, v14
	v_fma_f32 v12, v0, v14, -v10
	v_fma_f32 v13, v0, v15, v11
	v_add_f32_e32 v6, v12, v58
	v_add_f32_e32 v7, v13, v59
	global_store_dword v[8:9], v6, off offset:2304
	global_store_dword v[8:9], v7, off offset:2560
	v_mul_f32_e32 v10, v1, v7
	v_mul_f32_e32 v11, v1, v6
	v_fma_f32 v12, v0, v6, -v10
	v_fma_f32 v13, v0, v7, v11
	v_add_f32_e32 v14, v12, v60
	v_add_f32_e32 v15, v13, v61
	global_store_dword v[8:9], v14, off offset:2816
	global_store_dword v[8:9], v15, off offset:3072
	v_mul_f32_e32 v10, v1, v15
	v_mul_f32_e32 v11, v1, v14
	v_fma_f32 v12, v0, v14, -v10
	v_fma_f32 v13, v0, v15, v11
	v_add_f32_e32 v6, v12, v62
	v_add_f32_e32 v7, v13, v63
	s_waitcnt vmcnt(24)
	global_store_dword v[2:3], v6, off offset:-2816
	global_store_dword v[2:3], v7, off offset:-2560
	v_mul_f32_e32 v10, v1, v7
	v_mul_f32_e32 v11, v1, v6
	v_fma_f32 v12, v0, v6, -v10
	v_fma_f32 v13, v0, v7, v11
	v_add_f32_e32 v14, v12, v16
	v_add_f32_e32 v15, v13, v17
	global_store_dword v[2:3], v14, off offset:-2304
	global_store_dword v[2:3], v15, off offset:-2048
	v_mul_f32_e32 v10, v1, v15
	v_mul_f32_e32 v11, v1, v14
	v_fma_f32 v12, v0, v14, -v10
	v_fma_f32 v13, v0, v15, v11
	v_add_f32_e32 v6, v12, v18
	v_add_f32_e32 v7, v13, v19
	global_store_dword v[2:3], v6, off offset:-1792
	global_store_dword v[2:3], v7, off offset:-1536
	v_mul_f32_e32 v10, v1, v7
	v_mul_f32_e32 v11, v1, v6
	v_fma_f32 v12, v0, v6, -v10
	v_fma_f32 v13, v0, v7, v11
	v_add_f32_e32 v14, v12, v20
	v_add_f32_e32 v15, v13, v21
	global_store_dword v[2:3], v14, off offset:-1280
	global_store_dword v[2:3], v15, off offset:-1024
	v_mul_f32_e32 v10, v1, v15
	v_mul_f32_e32 v11, v1, v14
	v_fma_f32 v12, v0, v14, -v10
	v_fma_f32 v13, v0, v15, v11
	v_add_f32_e32 v6, v12, v22
	v_add_f32_e32 v7, v13, v23
	global_store_dword v[2:3], v6, off offset:-768
	global_store_dword v[2:3], v7, off offset:-512
	v_mul_f32_e32 v10, v1, v7
	v_mul_f32_e32 v11, v1, v6
	v_fma_f32 v12, v0, v6, -v10
	v_fma_f32 v13, v0, v7, v11
	v_add_f32_e32 v14, v12, v24
	v_add_f32_e32 v15, v13, v25
	global_store_dword v[2:3], v14, off offset:-256
	global_store_dword v[2:3], v15, off offset:0
	v_mul_f32_e32 v10, v1, v15
	v_mul_f32_e32 v11, v1, v14
	v_fma_f32 v12, v0, v14, -v10
	v_fma_f32 v13, v0, v15, v11
	v_add_f32_e32 v6, v12, v26
	v_add_f32_e32 v7, v13, v27
	global_store_dword v[2:3], v6, off offset:256
	global_store_dword v[2:3], v7, off offset:512
	v_mul_f32_e32 v10, v1, v7
	v_mul_f32_e32 v11, v1, v6
	v_fma_f32 v12, v0, v6, -v10
	v_fma_f32 v13, v0, v7, v11
	v_add_f32_e32 v14, v12, v28
	v_add_f32_e32 v15, v13, v29
	global_store_dword v[2:3], v14, off offset:768
	global_store_dword v[2:3], v15, off offset:1024
	v_mul_f32_e32 v10, v1, v15
	v_mul_f32_e32 v11, v1, v14
	v_fma_f32 v12, v0, v14, -v10
	v_fma_f32 v13, v0, v15, v11
	v_add_f32_e32 v6, v12, v30
	v_add_f32_e32 v7, v13, v31
	global_store_dword v[2:3], v6, off offset:1280
	global_store_dword v[2:3], v7, off offset:1536
	v_mul_f32_e32 v10, v1, v7
	v_mul_f32_e32 v11, v1, v6
	v_fma_f32 v12, v0, v6, -v10
	v_fma_f32 v13, v0, v7, v11
	v_add_f32_e32 v14, v12, v32
	v_add_f32_e32 v15, v13, v33
	global_store_dword v[2:3], v14, off offset:1792
	global_store_dword v[2:3], v15, off offset:2048
	v_mul_f32_e32 v10, v1, v15
	v_mul_f32_e32 v11, v1, v14
	v_fma_f32 v12, v0, v14, -v10
	v_fma_f32 v13, v0, v15, v11
	v_add_f32_e32 v6, v12, v34
	v_add_f32_e32 v7, v13, v35
	global_store_dword v[2:3], v6, off offset:2304
	global_store_dword v[2:3], v7, off offset:2560
	v_mul_f32_e32 v10, v1, v7
	v_mul_f32_e32 v11, v1, v6
	v_fma_f32 v12, v0, v6, -v10
	v_fma_f32 v13, v0, v7, v11
	v_add_f32_e32 v14, v12, v36
	v_add_f32_e32 v15, v13, v37
	global_store_dword v[2:3], v14, off offset:2816
	global_store_dword v[2:3], v15, off offset:3072
	v_mul_f32_e32 v10, v1, v15
	v_mul_f32_e32 v11, v1, v14
	v_fma_f32 v12, v0, v14, -v10
	v_fma_f32 v13, v0, v15, v11
	v_add_f32_e32 v6, v12, v38
	v_add_f32_e32 v7, v13, v39
	s_waitcnt vmcnt(0)
	s_mov_b64 s[12:13], exec
	s_mov_b64 exec, 1
	buffer_wbl2 sc1
	s_waitcnt vmcnt(0)
	v_readlane_b32 s10, v253, 2
	v_readlane_b32 s11, v253, 3
	s_lshl_b32 s14, s45, 8
	s_add_i32 s14, s14, 0xc2820
	s_add_u32 s10, s10, s14
	s_addc_u32 s11, s11, 0
	v_mov_b32_e32 v10, 1
	v_mov_b32_e32 v11, 0
	s_nop 3
	global_atomic_add v11, v10, s[10:11]
	s_mov_b64 exec, s[12:13]
	.p2align 6
